# gu supertile: nt cache hint on HID epilogue stores
# baseline (speedup 1.0000x reference)
; #define MFMA(a, b, c) __builtin_amdgcn_mfma_f32_32x32x16_bf16((a), (b), (c), 0, 0, 0)
; template <int AI, int BI>
; DI void gemm_tile(const u16* __restrict__ A, int lda, const u16* __restrict__ B, int ldb, int nk, bool swap,
;                   f32x16 (&acc)[AI][BI], char* lds) {
;     ...
;   for (int kt = 0; kt < nk; ++kt) {
;     const char* cur = lds + (kt & 1) * 32768;
;     if (kt + 1 < nk) gemm_stage<AI, BI>(A + (kt + 1) * 64, lda, B + (kt + 1) * 64, ldb, lds + ((kt + 1) & 1) * 32768, tid);
; #pragma unroll
;     for (int ks = 0; ks < 4; ++ks) {
;       const int co = ((ks * 2 + h) ^ sw) << 4;
;       s16x8 fa[AI], fb[BI];
; #pragma unroll
;       for (int i = 0; i < AI; ++i) fa[i] = *(const s16x8*)(cur + offA + i * 4096 + co);
; #pragma unroll
;       for (int i = 0; i < BI; ++i) fb[i] = *(const s16x8*)(cur + offB + i * 4096 + co);
; #pragma unroll
;       for (int i = 0; i < AI; ++i)
; #pragma unroll
;         for (int j = 0; j < BI; ++j) acc[i][j] = MFMA(fa[i], fb[j], acc[i][j]);
;     }
;     asm volatile("s_waitcnt vmcnt(0)" ::: "memory");
;     __syncthreads();
;   }
.Lgu1_kloop:
	s_waitcnt vmcnt(6)
	s_barrier
	ds_read_b128 v[114:117], v142 offset:0
	ds_read_b128 v[230:233], v144 offset:0
	ds_read_b128 v[234:237], v144 offset:2048
	ds_read_b128 v[118:121], v142 offset:2048
	ds_read_b128 v[134:137], v142 offset:8192
	ds_read_b128 v[138:141], v142 offset:10240
	ds_read_b128 v[238:241], v145 offset:0
	ds_read_b128 v[246:249], v145 offset:2048
	s_add_u32 m0, s18, 32768
	s_nop 0
	global_load_lds_dwordx4 v126, s[16:17]
	s_add_u32 m0, s18, 36864
	s_nop 0
	global_load_lds_dwordx4 v127, s[16:17]
	s_add_u32 m0, s18, 40960
	s_nop 0
	global_load_lds_dwordx4 v128, s[16:17]
	s_add_u32 m0, s18, 45056
	s_nop 0
	global_load_lds_dwordx4 v129, s[16:17]
	s_add_u32 m0, s18, 65664
	s_nop 0
	global_load_lds_dwordx4 v126, s[28:29]
	s_add_u32 m0, s18, 69760
	s_nop 0
	global_load_lds_dwordx4 v127, s[28:29]
	s_add_u32 s16, s16, 64
	s_addc_u32 s17, s17, 0
	s_add_u32 s28, s28, 64
	s_addc_u32 s29, s29, 0
	s_waitcnt lgkmcnt(6)
	v_mfma_f32_32x32x16_bf16 v[2:17], v[114:117], v[230:233], v[2:17]
	s_waitcnt lgkmcnt(5)
	v_mfma_f32_32x32x16_bf16 v[18:33], v[114:117], v[234:237], v[18:33]
	ds_read_b128 v[114:117], v143 offset:0
	s_waitcnt lgkmcnt(5)
	v_mfma_f32_32x32x16_bf16 v[34:49], v[118:121], v[230:233], v[34:49]
	v_mfma_f32_32x32x16_bf16 v[50:65], v[118:121], v[234:237], v[50:65]
	ds_read_b128 v[118:121], v143 offset:2048
	s_waitcnt lgkmcnt(5)
	v_mfma_f32_32x32x16_bf16 v[66:81], v[134:137], v[230:233], v[66:81]
	v_mfma_f32_32x32x16_bf16 v[82:97], v[134:137], v[234:237], v[82:97]
	ds_read_b128 v[134:137], v143 offset:8192
	s_waitcnt lgkmcnt(5)
	v_mfma_f32_32x32x16_bf16 v[98:113], v[138:141], v[230:233], v[98:113]
	v_mfma_f32_32x32x16_bf16 v[214:229], v[138:141], v[234:237], v[214:229]
	ds_read_b128 v[138:141], v143 offset:10240
	s_waitcnt lgkmcnt(3)
	v_mfma_f32_32x32x16_bf16 v[2:17], v[114:117], v[238:241], v[2:17]
	v_mfma_f32_32x32x16_bf16 v[18:33], v[114:117], v[246:249], v[18:33]
	s_waitcnt lgkmcnt(2)
	v_mfma_f32_32x32x16_bf16 v[34:49], v[118:121], v[238:241], v[34:49]
	v_mfma_f32_32x32x16_bf16 v[50:65], v[118:121], v[246:249], v[50:65]
	s_waitcnt lgkmcnt(1)
	v_mfma_f32_32x32x16_bf16 v[66:81], v[134:137], v[238:241], v[66:81]
	v_mfma_f32_32x32x16_bf16 v[82:97], v[134:137], v[246:249], v[82:97]
	s_waitcnt lgkmcnt(0)
	v_mfma_f32_32x32x16_bf16 v[98:113], v[138:141], v[238:241], v[98:113]
	v_mfma_f32_32x32x16_bf16 v[214:229], v[138:141], v[246:249], v[214:229]
	s_waitcnt vmcnt(6)
	s_barrier
	ds_read_b128 v[114:117], v142 offset:16384
	ds_read_b128 v[230:233], v144 offset:8192
	ds_read_b128 v[234:237], v144 offset:10240
	ds_read_b128 v[118:121], v142 offset:18432
	ds_read_b128 v[134:137], v142 offset:24576
	ds_read_b128 v[138:141], v142 offset:26624
	ds_read_b128 v[238:241], v145 offset:8192
	ds_read_b128 v[246:249], v145 offset:10240
	s_add_u32 m0, s18, 0
	s_nop 0
	global_load_lds_dwordx4 v126, s[16:17]
	s_add_u32 m0, s18, 4096
	s_nop 0
	global_load_lds_dwordx4 v127, s[16:17]
	s_add_u32 m0, s18, 8192
	s_nop 0
	global_load_lds_dwordx4 v128, s[16:17]
	s_add_u32 m0, s18, 12288
	s_nop 0
	global_load_lds_dwordx4 v129, s[16:17]
	s_add_u32 m0, s18, 49152
	s_nop 0
	global_load_lds_dwordx4 v126, s[28:29]
	s_add_u32 m0, s18, 53248
	s_nop 0
	global_load_lds_dwordx4 v127, s[28:29]
	s_add_u32 s16, s16, 64
	s_addc_u32 s17, s17, 0
	s_add_u32 s28, s28, 64
	s_addc_u32 s29, s29, 0
	s_waitcnt lgkmcnt(6)
	v_mfma_f32_32x32x16_bf16 v[2:17], v[114:117], v[230:233], v[2:17]
	s_waitcnt lgkmcnt(5)
	v_mfma_f32_32x32x16_bf16 v[18:33], v[114:117], v[234:237], v[18:33]
	ds_read_b128 v[114:117], v143 offset:16384
	s_waitcnt lgkmcnt(5)
	v_mfma_f32_32x32x16_bf16 v[34:49], v[118:121], v[230:233], v[34:49]
	v_mfma_f32_32x32x16_bf16 v[50:65], v[118:121], v[234:237], v[50:65]
	ds_read_b128 v[118:121], v143 offset:18432
	s_waitcnt lgkmcnt(5)
	v_mfma_f32_32x32x16_bf16 v[66:81], v[134:137], v[230:233], v[66:81]
	v_mfma_f32_32x32x16_bf16 v[82:97], v[134:137], v[234:237], v[82:97]
	ds_read_b128 v[134:137], v143 offset:24576
	s_waitcnt lgkmcnt(5)
	v_mfma_f32_32x32x16_bf16 v[98:113], v[138:141], v[230:233], v[98:113]
	v_mfma_f32_32x32x16_bf16 v[214:229], v[138:141], v[234:237], v[214:229]
	ds_read_b128 v[138:141], v143 offset:26624
	s_waitcnt lgkmcnt(3)
	v_mfma_f32_32x32x16_bf16 v[2:17], v[114:117], v[238:241], v[2:17]
	v_mfma_f32_32x32x16_bf16 v[18:33], v[114:117], v[246:249], v[18:33]
	s_waitcnt lgkmcnt(2)
	v_mfma_f32_32x32x16_bf16 v[34:49], v[118:121], v[238:241], v[34:49]
	v_mfma_f32_32x32x16_bf16 v[50:65], v[118:121], v[246:249], v[50:65]
	s_waitcnt lgkmcnt(1)
	v_mfma_f32_32x32x16_bf16 v[66:81], v[134:137], v[238:241], v[66:81]
	v_mfma_f32_32x32x16_bf16 v[82:97], v[134:137], v[246:249], v[82:97]
	s_waitcnt lgkmcnt(0)
	v_mfma_f32_32x32x16_bf16 v[98:113], v[138:141], v[238:241], v[98:113]
	v_mfma_f32_32x32x16_bf16 v[214:229], v[138:141], v[246:249], v[214:229]
	s_waitcnt vmcnt(6)
	s_barrier
; #define MFMA(a, b, c) __builtin_amdgcn_mfma_f32_32x32x16_bf16((a), (b), (c), 0, 0, 0)
; template <int AI, int BI>
; DI void gemm_tile(const u16* __restrict__ A, int lda, const u16* __restrict__ B, int ldb, int nk, bool swap,
;                   f32x16 (&acc)[AI][BI], char* lds) {
;     ...
;   for (int kt = 0; kt < nk; ++kt) {
;     const char* cur = lds + (kt & 1) * 32768;
;     if (kt + 1 < nk) gemm_stage<AI, BI>(A + (kt + 1) * 64, lda, B + (kt + 1) * 64, ldb, lds + ((kt + 1) & 1) * 32768, tid);
; #pragma unroll
;     for (int ks = 0; ks < 4; ++ks) {
;       const int co = ((ks * 2 + h) ^ sw) << 4;
;       s16x8 fa[AI], fb[BI];
; #pragma unroll
;       for (int i = 0; i < AI; ++i) fa[i] = *(const s16x8*)(cur + offA + i * 4096 + co);
; #pragma unroll
;       for (int i = 0; i < BI; ++i) fb[i] = *(const s16x8*)(cur + offB + i * 4096 + co);
; #pragma unroll
;       for (int i = 0; i < AI; ++i)
; #pragma unroll
;         for (int j = 0; j < BI; ++j) acc[i][j] = MFMA(fa[i], fb[j], acc[i][j]);
;     }
;     asm volatile("s_waitcnt vmcnt(0)" ::: "memory");
;     __syncthreads();
;   }
	ds_read_b128 v[114:117], v142 offset:32768
	ds_read_b128 v[230:233], v144 offset:16512
	ds_read_b128 v[234:237], v144 offset:18560
	ds_read_b128 v[118:121], v142 offset:34816
	ds_read_b128 v[134:137], v142 offset:40960
	ds_read_b128 v[138:141], v142 offset:43008
	ds_read_b128 v[238:241], v145 offset:16512
	ds_read_b128 v[246:249], v145 offset:18560
	s_add_u32 m0, s18, 16384
	s_nop 0
	global_load_lds_dwordx4 v126, s[16:17]
	s_add_u32 m0, s18, 20480
	s_nop 0
	global_load_lds_dwordx4 v127, s[16:17]
	s_add_u32 m0, s18, 24576
	s_nop 0
	global_load_lds_dwordx4 v128, s[16:17]
	s_add_u32 m0, s18, 28672
	s_nop 0
	global_load_lds_dwordx4 v129, s[16:17]
	s_add_u32 m0, s18, 57344
	s_nop 0
	global_load_lds_dwordx4 v126, s[28:29]
	s_add_u32 m0, s18, 61440
	s_nop 0
	global_load_lds_dwordx4 v127, s[28:29]
	s_add_u32 s16, s16, 64
	s_addc_u32 s17, s17, 0
	s_add_u32 s28, s28, 64
	s_addc_u32 s29, s29, 0
	s_waitcnt lgkmcnt(6)
	v_mfma_f32_32x32x16_bf16 v[2:17], v[114:117], v[230:233], v[2:17]
	s_waitcnt lgkmcnt(5)
	v_mfma_f32_32x32x16_bf16 v[18:33], v[114:117], v[234:237], v[18:33]
	ds_read_b128 v[114:117], v143 offset:32768
	s_waitcnt lgkmcnt(5)
	v_mfma_f32_32x32x16_bf16 v[34:49], v[118:121], v[230:233], v[34:49]
	v_mfma_f32_32x32x16_bf16 v[50:65], v[118:121], v[234:237], v[50:65]
	ds_read_b128 v[118:121], v143 offset:34816
	s_waitcnt lgkmcnt(5)
	v_mfma_f32_32x32x16_bf16 v[66:81], v[134:137], v[230:233], v[66:81]
	v_mfma_f32_32x32x16_bf16 v[82:97], v[134:137], v[234:237], v[82:97]
	ds_read_b128 v[134:137], v143 offset:40960
	s_waitcnt lgkmcnt(5)
	v_mfma_f32_32x32x16_bf16 v[98:113], v[138:141], v[230:233], v[98:113]
	v_mfma_f32_32x32x16_bf16 v[214:229], v[138:141], v[234:237], v[214:229]
	ds_read_b128 v[138:141], v143 offset:43008
	s_waitcnt lgkmcnt(3)
	v_mfma_f32_32x32x16_bf16 v[2:17], v[114:117], v[238:241], v[2:17]
	v_mfma_f32_32x32x16_bf16 v[18:33], v[114:117], v[246:249], v[18:33]
	s_waitcnt lgkmcnt(2)
	v_mfma_f32_32x32x16_bf16 v[34:49], v[118:121], v[238:241], v[34:49]
	v_mfma_f32_32x32x16_bf16 v[50:65], v[118:121], v[246:249], v[50:65]
	s_waitcnt lgkmcnt(1)
	v_mfma_f32_32x32x16_bf16 v[66:81], v[134:137], v[238:241], v[66:81]
	v_mfma_f32_32x32x16_bf16 v[82:97], v[134:137], v[246:249], v[82:97]
	s_waitcnt lgkmcnt(0)
	v_mfma_f32_32x32x16_bf16 v[98:113], v[138:141], v[238:241], v[98:113]
	v_mfma_f32_32x32x16_bf16 v[214:229], v[138:141], v[246:249], v[214:229]
	s_sub_u32 s36, s36, 1
	s_cmp_lg_u32 s36, 0
	s_cbranch_scc1 .Lgu1_kloop
	s_waitcnt vmcnt(6)
	s_barrier
	ds_read_b128 v[114:117], v142 offset:0
	ds_read_b128 v[230:233], v144 offset:0
	ds_read_b128 v[234:237], v144 offset:2048
	ds_read_b128 v[118:121], v142 offset:2048
	ds_read_b128 v[134:137], v142 offset:8192
	ds_read_b128 v[138:141], v142 offset:10240
	ds_read_b128 v[238:241], v145 offset:0
	ds_read_b128 v[246:249], v145 offset:2048
	s_waitcnt lgkmcnt(6)
	v_mfma_f32_32x32x16_bf16 v[2:17], v[114:117], v[230:233], v[2:17]
	s_waitcnt lgkmcnt(5)
	v_mfma_f32_32x32x16_bf16 v[18:33], v[114:117], v[234:237], v[18:33]
	ds_read_b128 v[114:117], v143 offset:0
	s_waitcnt lgkmcnt(5)
	v_mfma_f32_32x32x16_bf16 v[34:49], v[118:121], v[230:233], v[34:49]
	v_mfma_f32_32x32x16_bf16 v[50:65], v[118:121], v[234:237], v[50:65]
	ds_read_b128 v[118:121], v143 offset:2048
	s_waitcnt lgkmcnt(5)
	v_mfma_f32_32x32x16_bf16 v[66:81], v[134:137], v[230:233], v[66:81]
	v_mfma_f32_32x32x16_bf16 v[82:97], v[134:137], v[234:237], v[82:97]
	ds_read_b128 v[134:137], v143 offset:8192
	s_waitcnt lgkmcnt(5)
	v_mfma_f32_32x32x16_bf16 v[98:113], v[138:141], v[230:233], v[98:113]
	v_mfma_f32_32x32x16_bf16 v[214:229], v[138:141], v[234:237], v[214:229]
	ds_read_b128 v[138:141], v143 offset:10240
	s_waitcnt lgkmcnt(3)
	v_mfma_f32_32x32x16_bf16 v[2:17], v[114:117], v[238:241], v[2:17]
	v_mfma_f32_32x32x16_bf16 v[18:33], v[114:117], v[246:249], v[18:33]
	s_waitcnt lgkmcnt(2)
	v_mfma_f32_32x32x16_bf16 v[34:49], v[118:121], v[238:241], v[34:49]
	v_mfma_f32_32x32x16_bf16 v[50:65], v[118:121], v[246:249], v[50:65]
	s_waitcnt lgkmcnt(1)
	v_mfma_f32_32x32x16_bf16 v[66:81], v[134:137], v[238:241], v[66:81]
	v_mfma_f32_32x32x16_bf16 v[82:97], v[134:137], v[246:249], v[82:97]
	s_waitcnt lgkmcnt(0)
	v_mfma_f32_32x32x16_bf16 v[98:113], v[138:141], v[238:241], v[98:113]
	v_mfma_f32_32x32x16_bf16 v[214:229], v[138:141], v[246:249], v[214:229]
	s_waitcnt vmcnt(0)
	s_barrier
	ds_read_b128 v[114:117], v142 offset:16384
	ds_read_b128 v[230:233], v144 offset:8192
	ds_read_b128 v[234:237], v144 offset:10240
	ds_read_b128 v[118:121], v142 offset:18432
	ds_read_b128 v[134:137], v142 offset:24576
	ds_read_b128 v[138:141], v142 offset:26624
	ds_read_b128 v[238:241], v145 offset:8192
	ds_read_b128 v[246:249], v145 offset:10240
	s_waitcnt lgkmcnt(6)
	v_mfma_f32_32x32x16_bf16 v[2:17], v[114:117], v[230:233], v[2:17]
	s_waitcnt lgkmcnt(5)
	v_mfma_f32_32x32x16_bf16 v[18:33], v[114:117], v[234:237], v[18:33]
	ds_read_b128 v[114:117], v143 offset:16384
	s_waitcnt lgkmcnt(5)
	v_mfma_f32_32x32x16_bf16 v[34:49], v[118:121], v[230:233], v[34:49]
	v_mfma_f32_32x32x16_bf16 v[50:65], v[118:121], v[234:237], v[50:65]
	ds_read_b128 v[118:121], v143 offset:18432
	s_waitcnt lgkmcnt(5)
	v_mfma_f32_32x32x16_bf16 v[66:81], v[134:137], v[230:233], v[66:81]
	v_mfma_f32_32x32x16_bf16 v[82:97], v[134:137], v[234:237], v[82:97]
	ds_read_b128 v[134:137], v143 offset:24576
	s_waitcnt lgkmcnt(5)
	v_mfma_f32_32x32x16_bf16 v[98:113], v[138:141], v[230:233], v[98:113]
	v_mfma_f32_32x32x16_bf16 v[214:229], v[138:141], v[234:237], v[214:229]
	ds_read_b128 v[138:141], v143 offset:26624
	s_waitcnt lgkmcnt(3)
	v_mfma_f32_32x32x16_bf16 v[2:17], v[114:117], v[238:241], v[2:17]
	v_mfma_f32_32x32x16_bf16 v[18:33], v[114:117], v[246:249], v[18:33]
	s_waitcnt lgkmcnt(2)
	v_mfma_f32_32x32x16_bf16 v[34:49], v[118:121], v[238:241], v[34:49]
	v_mfma_f32_32x32x16_bf16 v[50:65], v[118:121], v[246:249], v[50:65]
	s_waitcnt lgkmcnt(1)
	v_mfma_f32_32x32x16_bf16 v[66:81], v[134:137], v[238:241], v[66:81]
	v_mfma_f32_32x32x16_bf16 v[82:97], v[134:137], v[246:249], v[82:97]
	s_waitcnt lgkmcnt(0)
	v_mfma_f32_32x32x16_bf16 v[98:113], v[138:141], v[238:241], v[98:113]
	v_mfma_f32_32x32x16_bf16 v[214:229], v[138:141], v[246:249], v[214:229]
	s_nop 7
	s_nop 7
	s_barrier
; template <int AI>
; DI void gu_tile(char* wsb, int sub, int m0, int n0, char* lds) {
;     ...
; #pragma unroll
;   for (int ai = 0; ai < AI; ++ai)
; #pragma unroll
;     for (int reg = 0; reg < 16; ++reg) {
;       float g = acc[ai][0][reg], u = acc[ai][1][reg];
;       float v = g * __builtin_amdgcn_rcpf(1.f + __expf(-g)) * u;
;       HIDu[ib + (unsigned)((ai * 32 + (reg & 3) + 8 * (reg >> 2)) * 2816)] = f2bf(v);
;       if ((reg & 7) == 7) __builtin_amdgcn_sched_barrier(0);
;     }
	v_mul_f32_e32 v250, 0xbfb8aa3b, v2
	v_mul_f32_e32 v252, 0xbfb8aa3b, v3
	v_exp_f32_e32 v250, v250
	v_exp_f32_e32 v252, v252
	v_add_u32_e32 v251, 0x0, v124
	v_add_f32_e32 v250, 1.0, v250
	v_add_f32_e32 v252, 1.0, v252
	v_rcp_f32_e32 v250, v250
	v_rcp_f32_e32 v252, v252
	v_add_u32_e32 v253, 0x1600, v124
	v_mul_f32_e32 v250, v2, v250
	v_mul_f32_e32 v252, v3, v252
	v_mul_f32_e32 v250, v18, v250
	v_mul_f32_e32 v252, v19, v252
	v_cvt_pk_bf16_f32 v250, v250, v250
	v_cvt_pk_bf16_f32 v252, v252, v252
	global_store_short v251, v250, s[34:35] nt
	global_store_short v253, v252, s[34:35] nt
	v_mul_f32_e32 v250, 0xbfb8aa3b, v4
	v_mul_f32_e32 v252, 0xbfb8aa3b, v5
	v_exp_f32_e32 v250, v250
	v_exp_f32_e32 v252, v252
	v_add_u32_e32 v251, 0x2c00, v124
	v_add_f32_e32 v250, 1.0, v250
	v_add_f32_e32 v252, 1.0, v252
	v_rcp_f32_e32 v250, v250
	v_rcp_f32_e32 v252, v252
	v_add_u32_e32 v253, 0x4200, v124
	v_mul_f32_e32 v250, v4, v250
	v_mul_f32_e32 v252, v5, v252
	v_mul_f32_e32 v250, v20, v250
	v_mul_f32_e32 v252, v21, v252
	v_cvt_pk_bf16_f32 v250, v250, v250
	v_cvt_pk_bf16_f32 v252, v252, v252
	global_store_short v251, v250, s[34:35] nt
	global_store_short v253, v252, s[34:35] nt
	v_mul_f32_e32 v250, 0xbfb8aa3b, v6
	v_mul_f32_e32 v252, 0xbfb8aa3b, v7
	v_exp_f32_e32 v250, v250
	v_exp_f32_e32 v252, v252
	v_add_u32_e32 v251, 0xb000, v124
	v_add_f32_e32 v250, 1.0, v250
	v_add_f32_e32 v252, 1.0, v252
	v_rcp_f32_e32 v250, v250
	v_rcp_f32_e32 v252, v252
	v_add_u32_e32 v253, 0xc600, v124
	v_mul_f32_e32 v250, v6, v250
	v_mul_f32_e32 v252, v7, v252
	v_mul_f32_e32 v250, v22, v250
	v_mul_f32_e32 v252, v23, v252
	v_cvt_pk_bf16_f32 v250, v250, v250
	v_cvt_pk_bf16_f32 v252, v252, v252
	global_store_short v251, v250, s[34:35] nt
	global_store_short v253, v252, s[34:35] nt
	v_mul_f32_e32 v250, 0xbfb8aa3b, v8
	v_mul_f32_e32 v252, 0xbfb8aa3b, v9
	v_exp_f32_e32 v250, v250
	v_exp_f32_e32 v252, v252
	v_add_u32_e32 v251, 0xdc00, v124
	v_add_f32_e32 v250, 1.0, v250
	v_add_f32_e32 v252, 1.0, v252
	v_rcp_f32_e32 v250, v250
	v_rcp_f32_e32 v252, v252
	v_add_u32_e32 v253, 0xf200, v124
	v_mul_f32_e32 v250, v8, v250
	v_mul_f32_e32 v252, v9, v252
	v_mul_f32_e32 v250, v24, v250
	v_mul_f32_e32 v252, v25, v252
	v_cvt_pk_bf16_f32 v250, v250, v250
	v_cvt_pk_bf16_f32 v252, v252, v252
	global_store_short v251, v250, s[34:35] nt
	global_store_short v253, v252, s[34:35] nt
	v_mul_f32_e32 v250, 0xbfb8aa3b, v10
	v_mul_f32_e32 v252, 0xbfb8aa3b, v11
	v_exp_f32_e32 v250, v250
	v_exp_f32_e32 v252, v252
	v_add_u32_e32 v251, 0x16000, v124
	v_add_f32_e32 v250, 1.0, v250
	v_add_f32_e32 v252, 1.0, v252
	v_rcp_f32_e32 v250, v250
	v_rcp_f32_e32 v252, v252
	v_add_u32_e32 v253, 0x17600, v124
	v_mul_f32_e32 v250, v10, v250
	v_mul_f32_e32 v252, v11, v252
	v_mul_f32_e32 v250, v26, v250
	v_mul_f32_e32 v252, v27, v252
	v_cvt_pk_bf16_f32 v250, v250, v250
	v_cvt_pk_bf16_f32 v252, v252, v252
	global_store_short v251, v250, s[34:35] nt
	global_store_short v253, v252, s[34:35] nt
	v_mul_f32_e32 v250, 0xbfb8aa3b, v12
	v_mul_f32_e32 v252, 0xbfb8aa3b, v13
	v_exp_f32_e32 v250, v250
	v_exp_f32_e32 v252, v252
	v_add_u32_e32 v251, 0x18c00, v124
	v_add_f32_e32 v250, 1.0, v250
	v_add_f32_e32 v252, 1.0, v252
	v_rcp_f32_e32 v250, v250
	v_rcp_f32_e32 v252, v252
	v_add_u32_e32 v253, 0x1a200, v124
	v_mul_f32_e32 v250, v12, v250
	v_mul_f32_e32 v252, v13, v252
	v_mul_f32_e32 v250, v28, v250
	v_mul_f32_e32 v252, v29, v252
	v_cvt_pk_bf16_f32 v250, v250, v250
	v_cvt_pk_bf16_f32 v252, v252, v252
	global_store_short v251, v250, s[34:35] nt
	global_store_short v253, v252, s[34:35] nt
	v_mul_f32_e32 v250, 0xbfb8aa3b, v14
	v_mul_f32_e32 v252, 0xbfb8aa3b, v15
	v_exp_f32_e32 v250, v250
	v_exp_f32_e32 v252, v252
	v_add_u32_e32 v251, 0x21000, v124
	v_add_f32_e32 v250, 1.0, v250
	v_add_f32_e32 v252, 1.0, v252
	v_rcp_f32_e32 v250, v250
	v_rcp_f32_e32 v252, v252
	v_add_u32_e32 v253, 0x22600, v124
	v_mul_f32_e32 v250, v14, v250
	v_mul_f32_e32 v252, v15, v252
	v_mul_f32_e32 v250, v30, v250
	v_mul_f32_e32 v252, v31, v252
	v_cvt_pk_bf16_f32 v250, v250, v250
	v_cvt_pk_bf16_f32 v252, v252, v252
	global_store_short v251, v250, s[34:35] nt
	global_store_short v253, v252, s[34:35] nt
	v_mul_f32_e32 v250, 0xbfb8aa3b, v16
	v_mul_f32_e32 v252, 0xbfb8aa3b, v17
	v_exp_f32_e32 v250, v250
	v_exp_f32_e32 v252, v252
	v_add_u32_e32 v251, 0x23c00, v124
	v_add_f32_e32 v250, 1.0, v250
	v_add_f32_e32 v252, 1.0, v252
	v_rcp_f32_e32 v250, v250
	v_rcp_f32_e32 v252, v252
	v_add_u32_e32 v253, 0x25200, v124
	v_mul_f32_e32 v250, v16, v250
	v_mul_f32_e32 v252, v17, v252
	v_mul_f32_e32 v250, v32, v250
	v_mul_f32_e32 v252, v33, v252
	v_cvt_pk_bf16_f32 v250, v250, v250
	v_cvt_pk_bf16_f32 v252, v252, v252
	global_store_short v251, v250, s[34:35] nt
	global_store_short v253, v252, s[34:35] nt
	v_mul_f32_e32 v250, 0xbfb8aa3b, v34
	v_mul_f32_e32 v252, 0xbfb8aa3b, v35
	v_exp_f32_e32 v250, v250
	v_exp_f32_e32 v252, v252
	v_add_u32_e32 v251, 0x2c000, v124
	v_add_f32_e32 v250, 1.0, v250
	v_add_f32_e32 v252, 1.0, v252
	v_rcp_f32_e32 v250, v250
	v_rcp_f32_e32 v252, v252
	v_add_u32_e32 v253, 0x2d600, v124
	v_mul_f32_e32 v250, v34, v250
	v_mul_f32_e32 v252, v35, v252
	v_mul_f32_e32 v250, v50, v250
	v_mul_f32_e32 v252, v51, v252
	v_cvt_pk_bf16_f32 v250, v250, v250
	v_cvt_pk_bf16_f32 v252, v252, v252
	global_store_short v251, v250, s[34:35] nt
	global_store_short v253, v252, s[34:35] nt
	v_mul_f32_e32 v250, 0xbfb8aa3b, v36
	v_mul_f32_e32 v252, 0xbfb8aa3b, v37
	v_exp_f32_e32 v250, v250
	v_exp_f32_e32 v252, v252
	v_add_u32_e32 v251, 0x2ec00, v124
	v_add_f32_e32 v250, 1.0, v250
	v_add_f32_e32 v252, 1.0, v252
	v_rcp_f32_e32 v250, v250
	v_rcp_f32_e32 v252, v252
	v_add_u32_e32 v253, 0x30200, v124
; template <int AI>
; DI void gu_tile(char* wsb, int sub, int m0, int n0, char* lds) {
;     ...
; #pragma unroll
;   for (int ai = 0; ai < AI; ++ai)
; #pragma unroll
;     for (int reg = 0; reg < 16; ++reg) {
;       float g = acc[ai][0][reg], u = acc[ai][1][reg];
;       float v = g * __builtin_amdgcn_rcpf(1.f + __expf(-g)) * u;
;       HIDu[ib + (unsigned)((ai * 32 + (reg & 3) + 8 * (reg >> 2)) * 2816)] = f2bf(v);
;       if ((reg & 7) == 7) __builtin_amdgcn_sched_barrier(0);
;     }
	v_mul_f32_e32 v250, v36, v250
	v_mul_f32_e32 v252, v37, v252
	v_mul_f32_e32 v250, v52, v250
	v_mul_f32_e32 v252, v53, v252
	v_cvt_pk_bf16_f32 v250, v250, v250
	v_cvt_pk_bf16_f32 v252, v252, v252
	global_store_short v251, v250, s[34:35] nt
	global_store_short v253, v252, s[34:35] nt
	v_mul_f32_e32 v250, 0xbfb8aa3b, v38
	v_mul_f32_e32 v252, 0xbfb8aa3b, v39
	v_exp_f32_e32 v250, v250
	v_exp_f32_e32 v252, v252
	v_add_u32_e32 v251, 0x37000, v124
	v_add_f32_e32 v250, 1.0, v250
	v_add_f32_e32 v252, 1.0, v252
	v_rcp_f32_e32 v250, v250
	v_rcp_f32_e32 v252, v252
	v_add_u32_e32 v253, 0x38600, v124
	v_mul_f32_e32 v250, v38, v250
	v_mul_f32_e32 v252, v39, v252
	v_mul_f32_e32 v250, v54, v250
	v_mul_f32_e32 v252, v55, v252
	v_cvt_pk_bf16_f32 v250, v250, v250
	v_cvt_pk_bf16_f32 v252, v252, v252
	global_store_short v251, v250, s[34:35] nt
	global_store_short v253, v252, s[34:35] nt
	v_mul_f32_e32 v250, 0xbfb8aa3b, v40
	v_mul_f32_e32 v252, 0xbfb8aa3b, v41
	v_exp_f32_e32 v250, v250
	v_exp_f32_e32 v252, v252
	v_add_u32_e32 v251, 0x39c00, v124
	v_add_f32_e32 v250, 1.0, v250
	v_add_f32_e32 v252, 1.0, v252
	v_rcp_f32_e32 v250, v250
	v_rcp_f32_e32 v252, v252
	v_add_u32_e32 v253, 0x3b200, v124
	v_mul_f32_e32 v250, v40, v250
	v_mul_f32_e32 v252, v41, v252
	v_mul_f32_e32 v250, v56, v250
	v_mul_f32_e32 v252, v57, v252
	v_cvt_pk_bf16_f32 v250, v250, v250
	v_cvt_pk_bf16_f32 v252, v252, v252
	global_store_short v251, v250, s[34:35] nt
	global_store_short v253, v252, s[34:35] nt
	v_mul_f32_e32 v250, 0xbfb8aa3b, v42
	v_mul_f32_e32 v252, 0xbfb8aa3b, v43
	v_exp_f32_e32 v250, v250
	v_exp_f32_e32 v252, v252
	v_add_u32_e32 v251, 0x42000, v124
	v_add_f32_e32 v250, 1.0, v250
	v_add_f32_e32 v252, 1.0, v252
	v_rcp_f32_e32 v250, v250
	v_rcp_f32_e32 v252, v252
	v_add_u32_e32 v253, 0x43600, v124
	v_mul_f32_e32 v250, v42, v250
	v_mul_f32_e32 v252, v43, v252
	v_mul_f32_e32 v250, v58, v250
	v_mul_f32_e32 v252, v59, v252
	v_cvt_pk_bf16_f32 v250, v250, v250
	v_cvt_pk_bf16_f32 v252, v252, v252
	global_store_short v251, v250, s[34:35] nt
	global_store_short v253, v252, s[34:35] nt
	v_mul_f32_e32 v250, 0xbfb8aa3b, v44
	v_mul_f32_e32 v252, 0xbfb8aa3b, v45
	v_exp_f32_e32 v250, v250
	v_exp_f32_e32 v252, v252
	v_add_u32_e32 v251, 0x44c00, v124
	v_add_f32_e32 v250, 1.0, v250
	v_add_f32_e32 v252, 1.0, v252
	v_rcp_f32_e32 v250, v250
	v_rcp_f32_e32 v252, v252
	v_add_u32_e32 v253, 0x46200, v124
	v_mul_f32_e32 v250, v44, v250
	v_mul_f32_e32 v252, v45, v252
	v_mul_f32_e32 v250, v60, v250
	v_mul_f32_e32 v252, v61, v252
	v_cvt_pk_bf16_f32 v250, v250, v250
	v_cvt_pk_bf16_f32 v252, v252, v252
	global_store_short v251, v250, s[34:35] nt
	global_store_short v253, v252, s[34:35] nt
	v_mul_f32_e32 v250, 0xbfb8aa3b, v46
	v_mul_f32_e32 v252, 0xbfb8aa3b, v47
	v_exp_f32_e32 v250, v250
	v_exp_f32_e32 v252, v252
	v_add_u32_e32 v251, 0x4d000, v124
	v_add_f32_e32 v250, 1.0, v250
	v_add_f32_e32 v252, 1.0, v252
	v_rcp_f32_e32 v250, v250
	v_rcp_f32_e32 v252, v252
	v_add_u32_e32 v253, 0x4e600, v124
	v_mul_f32_e32 v250, v46, v250
	v_mul_f32_e32 v252, v47, v252
	v_mul_f32_e32 v250, v62, v250
	v_mul_f32_e32 v252, v63, v252
	v_cvt_pk_bf16_f32 v250, v250, v250
	v_cvt_pk_bf16_f32 v252, v252, v252
	global_store_short v251, v250, s[34:35] nt
	global_store_short v253, v252, s[34:35] nt
	v_mul_f32_e32 v250, 0xbfb8aa3b, v48
	v_mul_f32_e32 v252, 0xbfb8aa3b, v49
	v_exp_f32_e32 v250, v250
	v_exp_f32_e32 v252, v252
	v_add_u32_e32 v251, 0x4fc00, v124
	v_add_f32_e32 v250, 1.0, v250
	v_add_f32_e32 v252, 1.0, v252
	v_rcp_f32_e32 v250, v250
	v_rcp_f32_e32 v252, v252
	v_add_u32_e32 v253, 0x51200, v124
	v_mul_f32_e32 v250, v48, v250
	v_mul_f32_e32 v252, v49, v252
	v_mul_f32_e32 v250, v64, v250
	v_mul_f32_e32 v252, v65, v252
	v_cvt_pk_bf16_f32 v250, v250, v250
	v_cvt_pk_bf16_f32 v252, v252, v252
	global_store_short v251, v250, s[34:35] nt
	global_store_short v253, v252, s[34:35] nt
	v_mul_f32_e32 v250, 0xbfb8aa3b, v66
	v_mul_f32_e32 v252, 0xbfb8aa3b, v67
	v_exp_f32_e32 v250, v250
	v_exp_f32_e32 v252, v252
	v_add_u32_e32 v251, 0xb0000, v124
	v_add_f32_e32 v250, 1.0, v250
	v_add_f32_e32 v252, 1.0, v252
	v_rcp_f32_e32 v250, v250
	v_rcp_f32_e32 v252, v252
	v_add_u32_e32 v253, 0xb1600, v124
	v_mul_f32_e32 v250, v66, v250
	v_mul_f32_e32 v252, v67, v252
	v_mul_f32_e32 v250, v82, v250
	v_mul_f32_e32 v252, v83, v252
	v_cvt_pk_bf16_f32 v250, v250, v250
	v_cvt_pk_bf16_f32 v252, v252, v252
	global_store_short v251, v250, s[34:35] nt
	global_store_short v253, v252, s[34:35] nt
	v_mul_f32_e32 v250, 0xbfb8aa3b, v68
	v_mul_f32_e32 v252, 0xbfb8aa3b, v69
	v_exp_f32_e32 v250, v250
	v_exp_f32_e32 v252, v252
	v_add_u32_e32 v251, 0xb2c00, v124
	v_add_f32_e32 v250, 1.0, v250
	v_add_f32_e32 v252, 1.0, v252
	v_rcp_f32_e32 v250, v250
	v_rcp_f32_e32 v252, v252
	v_add_u32_e32 v253, 0xb4200, v124
	v_mul_f32_e32 v250, v68, v250
	v_mul_f32_e32 v252, v69, v252
	v_mul_f32_e32 v250, v84, v250
	v_mul_f32_e32 v252, v85, v252
	v_cvt_pk_bf16_f32 v250, v250, v250
	v_cvt_pk_bf16_f32 v252, v252, v252
	global_store_short v251, v250, s[34:35] nt
	global_store_short v253, v252, s[34:35] nt
	v_mul_f32_e32 v250, 0xbfb8aa3b, v70
	v_mul_f32_e32 v252, 0xbfb8aa3b, v71
	v_exp_f32_e32 v250, v250
	v_exp_f32_e32 v252, v252
	v_add_u32_e32 v251, 0xbb000, v124
	v_add_f32_e32 v250, 1.0, v250
	v_add_f32_e32 v252, 1.0, v252
	v_rcp_f32_e32 v250, v250
	v_rcp_f32_e32 v252, v252
	v_add_u32_e32 v253, 0xbc600, v124
	v_mul_f32_e32 v250, v70, v250
	v_mul_f32_e32 v252, v71, v252
	v_mul_f32_e32 v250, v86, v250
	v_mul_f32_e32 v252, v87, v252
	v_cvt_pk_bf16_f32 v250, v250, v250
	v_cvt_pk_bf16_f32 v252, v252, v252
	global_store_short v251, v250, s[34:35] nt
	global_store_short v253, v252, s[34:35] nt
; template <int AI>
; DI void gu_tile(char* wsb, int sub, int m0, int n0, char* lds) {
;     ...
; #pragma unroll
;   for (int ai = 0; ai < AI; ++ai)
; #pragma unroll
;     for (int reg = 0; reg < 16; ++reg) {
;       float g = acc[ai][0][reg], u = acc[ai][1][reg];
;       float v = g * __builtin_amdgcn_rcpf(1.f + __expf(-g)) * u;
;       HIDu[ib + (unsigned)((ai * 32 + (reg & 3) + 8 * (reg >> 2)) * 2816)] = f2bf(v);
;       if ((reg & 7) == 7) __builtin_amdgcn_sched_barrier(0);
;     }
	v_mul_f32_e32 v250, 0xbfb8aa3b, v72
	v_mul_f32_e32 v252, 0xbfb8aa3b, v73
	v_exp_f32_e32 v250, v250
	v_exp_f32_e32 v252, v252
	v_add_u32_e32 v251, 0xbdc00, v124
	v_add_f32_e32 v250, 1.0, v250
	v_add_f32_e32 v252, 1.0, v252
	v_rcp_f32_e32 v250, v250
	v_rcp_f32_e32 v252, v252
	v_add_u32_e32 v253, 0xbf200, v124
	v_mul_f32_e32 v250, v72, v250
	v_mul_f32_e32 v252, v73, v252
	v_mul_f32_e32 v250, v88, v250
	v_mul_f32_e32 v252, v89, v252
	v_cvt_pk_bf16_f32 v250, v250, v250
	v_cvt_pk_bf16_f32 v252, v252, v252
	global_store_short v251, v250, s[34:35] nt
	global_store_short v253, v252, s[34:35] nt
	v_mul_f32_e32 v250, 0xbfb8aa3b, v74
	v_mul_f32_e32 v252, 0xbfb8aa3b, v75
	v_exp_f32_e32 v250, v250
	v_exp_f32_e32 v252, v252
	v_add_u32_e32 v251, 0xc6000, v124
	v_add_f32_e32 v250, 1.0, v250
	v_add_f32_e32 v252, 1.0, v252
	v_rcp_f32_e32 v250, v250
	v_rcp_f32_e32 v252, v252
	v_add_u32_e32 v253, 0xc7600, v124
	v_mul_f32_e32 v250, v74, v250
	v_mul_f32_e32 v252, v75, v252
	v_mul_f32_e32 v250, v90, v250
	v_mul_f32_e32 v252, v91, v252
	v_cvt_pk_bf16_f32 v250, v250, v250
	v_cvt_pk_bf16_f32 v252, v252, v252
	global_store_short v251, v250, s[34:35] nt
	global_store_short v253, v252, s[34:35] nt
	v_mul_f32_e32 v250, 0xbfb8aa3b, v76
	v_mul_f32_e32 v252, 0xbfb8aa3b, v77
	v_exp_f32_e32 v250, v250
	v_exp_f32_e32 v252, v252
	v_add_u32_e32 v251, 0xc8c00, v124
	v_add_f32_e32 v250, 1.0, v250
	v_add_f32_e32 v252, 1.0, v252
	v_rcp_f32_e32 v250, v250
	v_rcp_f32_e32 v252, v252
	v_add_u32_e32 v253, 0xca200, v124
	v_mul_f32_e32 v250, v76, v250
	v_mul_f32_e32 v252, v77, v252
	v_mul_f32_e32 v250, v92, v250
	v_mul_f32_e32 v252, v93, v252
	v_cvt_pk_bf16_f32 v250, v250, v250
	v_cvt_pk_bf16_f32 v252, v252, v252
	global_store_short v251, v250, s[34:35] nt
	global_store_short v253, v252, s[34:35] nt
	v_mul_f32_e32 v250, 0xbfb8aa3b, v78
	v_mul_f32_e32 v252, 0xbfb8aa3b, v79
	v_exp_f32_e32 v250, v250
	v_exp_f32_e32 v252, v252
	v_add_u32_e32 v251, 0xd1000, v124
	v_add_f32_e32 v250, 1.0, v250
	v_add_f32_e32 v252, 1.0, v252
	v_rcp_f32_e32 v250, v250
	v_rcp_f32_e32 v252, v252
	v_add_u32_e32 v253, 0xd2600, v124
	v_mul_f32_e32 v250, v78, v250
	v_mul_f32_e32 v252, v79, v252
	v_mul_f32_e32 v250, v94, v250
	v_mul_f32_e32 v252, v95, v252
	v_cvt_pk_bf16_f32 v250, v250, v250
	v_cvt_pk_bf16_f32 v252, v252, v252
	global_store_short v251, v250, s[34:35] nt
	global_store_short v253, v252, s[34:35] nt
	v_mul_f32_e32 v250, 0xbfb8aa3b, v80
	v_mul_f32_e32 v252, 0xbfb8aa3b, v81
	v_exp_f32_e32 v250, v250
	v_exp_f32_e32 v252, v252
	v_add_u32_e32 v251, 0xd3c00, v124
	v_add_f32_e32 v250, 1.0, v250
	v_add_f32_e32 v252, 1.0, v252
	v_rcp_f32_e32 v250, v250
	v_rcp_f32_e32 v252, v252
	v_add_u32_e32 v253, 0xd5200, v124
	v_mul_f32_e32 v250, v80, v250
	v_mul_f32_e32 v252, v81, v252
	v_mul_f32_e32 v250, v96, v250
	v_mul_f32_e32 v252, v97, v252
	v_cvt_pk_bf16_f32 v250, v250, v250
	v_cvt_pk_bf16_f32 v252, v252, v252
	global_store_short v251, v250, s[34:35] nt
	global_store_short v253, v252, s[34:35] nt
	v_mul_f32_e32 v250, 0xbfb8aa3b, v98
	v_mul_f32_e32 v252, 0xbfb8aa3b, v99
	v_exp_f32_e32 v250, v250
	v_exp_f32_e32 v252, v252
	v_add_u32_e32 v251, 0xdc000, v124
	v_add_f32_e32 v250, 1.0, v250
	v_add_f32_e32 v252, 1.0, v252
	v_rcp_f32_e32 v250, v250
	v_rcp_f32_e32 v252, v252
	v_add_u32_e32 v253, 0xdd600, v124
	v_mul_f32_e32 v250, v98, v250
	v_mul_f32_e32 v252, v99, v252
	v_mul_f32_e32 v250, v214, v250
	v_mul_f32_e32 v252, v215, v252
	v_cvt_pk_bf16_f32 v250, v250, v250
	v_cvt_pk_bf16_f32 v252, v252, v252
	global_store_short v251, v250, s[34:35] nt
	global_store_short v253, v252, s[34:35] nt
	v_mul_f32_e32 v250, 0xbfb8aa3b, v100
	v_mul_f32_e32 v252, 0xbfb8aa3b, v101
	v_exp_f32_e32 v250, v250
	v_exp_f32_e32 v252, v252
	v_add_u32_e32 v251, 0xdec00, v124
	v_add_f32_e32 v250, 1.0, v250
	v_add_f32_e32 v252, 1.0, v252
	v_rcp_f32_e32 v250, v250
	v_rcp_f32_e32 v252, v252
	v_add_u32_e32 v253, 0xe0200, v124
	v_mul_f32_e32 v250, v100, v250
	v_mul_f32_e32 v252, v101, v252
	v_mul_f32_e32 v250, v216, v250
	v_mul_f32_e32 v252, v217, v252
	v_cvt_pk_bf16_f32 v250, v250, v250
	v_cvt_pk_bf16_f32 v252, v252, v252
; template <int AI>
; DI void gu_tile(char* wsb, int sub, int m0, int n0, char* lds) {
;     ...
; #pragma unroll
;   for (int ai = 0; ai < AI; ++ai)
; #pragma unroll
;     for (int reg = 0; reg < 16; ++reg) {
;       float g = acc[ai][0][reg], u = acc[ai][1][reg];
;       float v = g * __builtin_amdgcn_rcpf(1.f + __expf(-g)) * u;
;       HIDu[ib + (unsigned)((ai * 32 + (reg & 3) + 8 * (reg >> 2)) * 2816)] = f2bf(v);
;       if ((reg & 7) == 7) __builtin_amdgcn_sched_barrier(0);
;     }
; DI void phase_gu(const Params& p, char* wsb, int sub, int mrows, char* lds) {
;     ...
;   for (int rnd = 0; next_tile(rnd, 128, 44, mt, nt); ++rnd) gu_tile<2>(wsb, sub, mt * 128, nt * 128, lds);
;   if (mrows > TL)
;     for (int rnd = 0; next_tile(rnd, 32, 44, mt, nt); ++rnd) gu_tile<1>(wsb, sub, TL + mt * 64, nt * 128, lds);
	global_store_short v251, v250, s[34:35] nt
	global_store_short v253, v252, s[34:35] nt
	v_mul_f32_e32 v250, 0xbfb8aa3b, v102
	v_mul_f32_e32 v252, 0xbfb8aa3b, v103
	v_exp_f32_e32 v250, v250
	v_exp_f32_e32 v252, v252
	v_add_u32_e32 v251, 0xe7000, v124
	v_add_f32_e32 v250, 1.0, v250
	v_add_f32_e32 v252, 1.0, v252
	v_rcp_f32_e32 v250, v250
	v_rcp_f32_e32 v252, v252
	v_add_u32_e32 v253, 0xe8600, v124
	v_mul_f32_e32 v250, v102, v250
	v_mul_f32_e32 v252, v103, v252
	v_mul_f32_e32 v250, v218, v250
	v_mul_f32_e32 v252, v219, v252
	v_cvt_pk_bf16_f32 v250, v250, v250
	v_cvt_pk_bf16_f32 v252, v252, v252
	global_store_short v251, v250, s[34:35] nt
	global_store_short v253, v252, s[34:35] nt
	v_mul_f32_e32 v250, 0xbfb8aa3b, v104
	v_mul_f32_e32 v252, 0xbfb8aa3b, v105
	v_exp_f32_e32 v250, v250
	v_exp_f32_e32 v252, v252
	v_add_u32_e32 v251, 0xe9c00, v124
	v_add_f32_e32 v250, 1.0, v250
	v_add_f32_e32 v252, 1.0, v252
	v_rcp_f32_e32 v250, v250
	v_rcp_f32_e32 v252, v252
	v_add_u32_e32 v253, 0xeb200, v124
	v_mul_f32_e32 v250, v104, v250
	v_mul_f32_e32 v252, v105, v252
	v_mul_f32_e32 v250, v220, v250
	v_mul_f32_e32 v252, v221, v252
	v_cvt_pk_bf16_f32 v250, v250, v250
	v_cvt_pk_bf16_f32 v252, v252, v252
	global_store_short v251, v250, s[34:35] nt
	global_store_short v253, v252, s[34:35] nt
	v_mul_f32_e32 v250, 0xbfb8aa3b, v106
	v_mul_f32_e32 v252, 0xbfb8aa3b, v107
	v_exp_f32_e32 v250, v250
	v_exp_f32_e32 v252, v252
	v_add_u32_e32 v251, 0xf2000, v124
	v_add_f32_e32 v250, 1.0, v250
	v_add_f32_e32 v252, 1.0, v252
	v_rcp_f32_e32 v250, v250
	v_rcp_f32_e32 v252, v252
	v_add_u32_e32 v253, 0xf3600, v124
	v_mul_f32_e32 v250, v106, v250
	v_mul_f32_e32 v252, v107, v252
	v_mul_f32_e32 v250, v222, v250
	v_mul_f32_e32 v252, v223, v252
	v_cvt_pk_bf16_f32 v250, v250, v250
	v_cvt_pk_bf16_f32 v252, v252, v252
	global_store_short v251, v250, s[34:35] nt
	global_store_short v253, v252, s[34:35] nt
	v_mul_f32_e32 v250, 0xbfb8aa3b, v108
	v_mul_f32_e32 v252, 0xbfb8aa3b, v109
	v_exp_f32_e32 v250, v250
	v_exp_f32_e32 v252, v252
	v_add_u32_e32 v251, 0xf4c00, v124
	v_add_f32_e32 v250, 1.0, v250
	v_add_f32_e32 v252, 1.0, v252
	v_rcp_f32_e32 v250, v250
	v_rcp_f32_e32 v252, v252
	v_add_u32_e32 v253, 0xf6200, v124
	v_mul_f32_e32 v250, v108, v250
	v_mul_f32_e32 v252, v109, v252
	v_mul_f32_e32 v250, v224, v250
	v_mul_f32_e32 v252, v225, v252
	v_cvt_pk_bf16_f32 v250, v250, v250
	v_cvt_pk_bf16_f32 v252, v252, v252
	global_store_short v251, v250, s[34:35] nt
	global_store_short v253, v252, s[34:35] nt
	v_mul_f32_e32 v250, 0xbfb8aa3b, v110
	v_mul_f32_e32 v252, 0xbfb8aa3b, v111
	v_exp_f32_e32 v250, v250
	v_exp_f32_e32 v252, v252
	v_add_u32_e32 v251, 0xfd000, v124
	v_add_f32_e32 v250, 1.0, v250
	v_add_f32_e32 v252, 1.0, v252
	v_rcp_f32_e32 v250, v250
	v_rcp_f32_e32 v252, v252
	v_add_u32_e32 v253, 0xfe600, v124
	v_mul_f32_e32 v250, v110, v250
	v_mul_f32_e32 v252, v111, v252
	v_mul_f32_e32 v250, v226, v250
	v_mul_f32_e32 v252, v227, v252
	v_cvt_pk_bf16_f32 v250, v250, v250
	v_cvt_pk_bf16_f32 v252, v252, v252
	global_store_short v251, v250, s[34:35] nt
	global_store_short v253, v252, s[34:35] nt
	v_mul_f32_e32 v250, 0xbfb8aa3b, v112
	v_mul_f32_e32 v252, 0xbfb8aa3b, v113
	v_exp_f32_e32 v250, v250
	v_exp_f32_e32 v252, v252
	v_add_u32_e32 v251, 0xffc00, v124
	v_add_f32_e32 v250, 1.0, v250
	v_add_f32_e32 v252, 1.0, v252
	v_rcp_f32_e32 v250, v250
	v_rcp_f32_e32 v252, v252
	v_add_u32_e32 v253, 0x101200, v124
	v_mul_f32_e32 v250, v112, v250
	v_mul_f32_e32 v252, v113, v252
	v_mul_f32_e32 v250, v228, v250
	v_mul_f32_e32 v252, v229, v252
	v_cvt_pk_bf16_f32 v250, v250, v250
	v_cvt_pk_bf16_f32 v252, v252, v252
	global_store_short v251, v250, s[34:35] nt
	global_store_short v253, v252, s[34:35] nt
	s_add_u32 s32, s32, 1
	s_cmp_lt_u32 s32, 5
	s_cbranch_scc1 .Lgu1_round
	s_lshr_b32 s37, s40, 4
	s_add_u32 s37, s37, 40
	s_and_b32 s50, s40, 15
	s_lshl_b32 s51, s41, 4
	s_add_u32 s50, s50, s51
	s_lshr_b32 s51, s50, 3
	s_mul_i32 s51, s51, 0x160
	s_lshl_b32 s52, s37, 3
	s_add_u32 s51, s51, s52
	s_and_b32 s52, s50, 7
	s_add_u32 s14, s51, s52
	s_lshl_b32 s15, s14, 7
	s_mov_b32 s52, 1
	v_writelane_b32 v245, s52, 0
